# P1 conversion classes without a convert-first class: 3/8 between the GEMM1 calls, 5/8 after
# speedup vs baseline: 1.0013x; 1.0013x over previous
_Z3fwd4Args:
	v_writelane_b32 v249, s0, 0
	v_writelane_b32 v249, s1, 1
	v_writelane_b32 v249, s2, 2
	v_mov_b32_e32 v250, v0
	s_and_b32 s98, s2, 7
	s_movk_i32 s101, 0x100
	s_cmp_lt_u32 s98, 3
	s_cselect_b32 s101, 0x400, s101
	s_cmp_lt_u32 s98, 0
	s_cselect_b32 s101, 0, s101
